# scan stepper fully unrolled per 16-step chunk, trimmed chunk preheader
# speedup vs baseline: 1.0457x; 1.0195x over previous
; #define LAS __attribute__((address_space(3)))
; __device__ __forceinline__ void scan_job(LAS unsigned char* lds, const AP a, int l, int bl, int hd, int rh) {
;     ...
;             const LAS float* bp = vec + (ch & 1) * BUFSZ; LAS float* yl = Yp + (ch & 1) * YBUF + jq * YSTR + 2 * srow;
;             const int o0 = jq * 4, vo = 3 * VSZ + rh * 32 + 2 * srow;
;             f32x4 rN = *(const LAS f32x4*)(bp + o0), wN = *(const LAS f32x4*)(bp + VSZ + o0), kN = *(const LAS f32x4*)(bp + 2 * VSZ + o0), kkN = *(const LAS f32x4*)(bp + 4 * VSZ + o0), bN = *(const LAS f32x4*)(bp + 5 * VSZ + o0);
;             f32x2 vN = *(const LAS f32x2*)(bp + vo);
; #pragma unroll 4
;             for (int st = 0; st < CH; ++st) {
;                 const f32x4 w = wN, kk = kkN, b = bN, k = kN, r = rN; const f32x2 v = vN;
;                 const int on = ((st + 1) & (CH - 1)) * 64;
;                 rN = *(const LAS f32x4*)(bp + on + o0); wN = *(const LAS f32x4*)(bp + VSZ + on + o0); kN = *(const LAS f32x4*)(bp + 2 * VSZ + on + o0); kkN = *(const LAS f32x4*)(bp + 4 * VSZ + on + o0); bN = *(const LAS f32x4*)(bp + 5 * VSZ + on + o0);
;                 vN = *(const LAS f32x2*)(bp + on + vo);
;                 const f32x2 kk0 = {kk.x, kk.y}, kk1 = {kk.z, kk.w}, w0 = {w.x, w.y}, w1 = {w.z, w.w}, b0 = {b.x, b.y}, b1 = {b.z, b.w}, k0 = {k.x, k.y}, k1 = {k.z, k.w}, r0 = {r.x, r.y}, r1 = {r.z, r.w};
;                 const f32x2 va = {v.x, v.x}, vb = {v.y, v.y};
;                 const f32x2 pa = sA0 * kk0 + sA1 * kk1, pb = sB0 * kk0 + sB1 * kk1;
;                 const float saA = -red16(pa.x + pa.y), saB = -red16(pb.x + pb.y);
;                 const f32x2 sav = {saA, saA}, sbv = {saB, saB};
;                 sA0 = sA0 * w0 + (sav * b0 + va * k0); sA1 = sA1 * w1 + (sav * b1 + va * k1);
;                 sB0 = sB0 * w0 + (sbv * b0 + vb * k0); sB1 = sB1 * w1 + (sbv * b1 + vb * k1);
;                 const f32x2 ya = sA0 * r0 + sA1 * r1, yb = sB0 * r0 + sB1 * r1;
;                 *(LAS f32x2*)(yl + st * 16 * YSTR) = (f32x2){ya.x + ya.y, yb.x + yb.y};
.LBB0_250:
	s_and_saveexec_b64 s[14:15], s[40:41]
	s_xor_b64 s[20:21], exec, s[14:15]
	s_cbranch_execz .LBB0_254
	s_and_b32 s14, s12, 1
	s_and_b32 s17, s12, 1
	s_mulk_i32 s14, 0x6000
	s_mul_i32 s17, s17, 0x8800
	v_lshl_add_u32 v0, v67, 2, s14
	v_lshl_add_u32 v95, v89, 2, s14
	v_add_u32_e32 v96, s17, v94
	s_setprio 3
	ds_read_b128 v[26:29], v0
	ds_read_b128 v[30:33], v0 offset:4096
	ds_read_b128 v[34:37], v0 offset:8192
	ds_read_b128 v[42:45], v0 offset:16384
	ds_read_b128 v[38:41], v0 offset:20480
	ds_read_b64 v[82:83], v95 offset:12288
	s_waitcnt lgkmcnt(0)
	ds_read_b128 v[46:49], v0 offset:256
	ds_read_b128 v[50:53], v0 offset:4352
	ds_read_b128 v[54:57], v0 offset:8448
	ds_read_b128 v[62:65], v0 offset:16640
	ds_read_b128 v[58:61], v0 offset:20736
	ds_read_b64 v[84:85], v95 offset:12544
	v_pk_mul_f32 v[112:113], v[74:75], v[42:43] op_sel_hi:[1,0]
	v_pk_mul_f32 v[104:105], v[82:83], v[34:35] op_sel_hi:[1,0]
	v_pk_fma_f32 v[112:113], v[76:77], v[42:43], v[112:113] op_sel:[0,1,0]
	v_pk_mul_f32 v[106:107], v[82:83], v[34:35] op_sel:[0,1]
	v_pk_fma_f32 v[112:113], v[78:79], v[44:45], v[112:113] op_sel_hi:[1,0,1]
	v_pk_mul_f32 v[108:109], v[82:83], v[36:37] op_sel_hi:[1,0]
	v_pk_fma_f32 v[112:113], v[80:81], v[44:45], v[112:113] op_sel:[0,1,0]
	v_pk_mul_f32 v[110:111], v[82:83], v[36:37] op_sel:[0,1]
	v_pk_fma_f32 v[104:105], v[74:75], v[30:31], v[104:105] op_sel_hi:[1,0,1]
	v_add_f32_dpp v112, v112, v112 quad_perm:[1,0,3,2] row_mask:0xf bank_mask:0xf bound_ctrl:1
	v_add_f32_dpp v113, v113, v113 quad_perm:[1,0,3,2] row_mask:0xf bank_mask:0xf bound_ctrl:1
	v_pk_fma_f32 v[106:107], v[76:77], v[30:31], v[106:107] op_sel:[0,1,0]
	v_add_f32_dpp v112, v112, v112 quad_perm:[2,3,0,1] row_mask:0xf bank_mask:0xf bound_ctrl:1
	v_add_f32_dpp v113, v113, v113 quad_perm:[2,3,0,1] row_mask:0xf bank_mask:0xf bound_ctrl:1
	v_pk_fma_f32 v[108:109], v[78:79], v[32:33], v[108:109] op_sel_hi:[1,0,1]
	v_add_f32_dpp v112, v112, v112 row_half_mirror row_mask:0xf bank_mask:0xf bound_ctrl:1
	v_add_f32_dpp v113, v113, v113 row_half_mirror row_mask:0xf bank_mask:0xf bound_ctrl:1
	v_pk_fma_f32 v[110:111], v[80:81], v[32:33], v[110:111] op_sel:[0,1,0]
	v_add_f32_dpp v112, v112, v112 row_mirror row_mask:0xf bank_mask:0xf bound_ctrl:1
	v_add_f32_dpp v113, v113, v113 row_mirror row_mask:0xf bank_mask:0xf bound_ctrl:1
	v_pk_fma_f32 v[74:75], v[112:113], v[38:39], v[104:105] op_sel_hi:[1,0,1] neg_lo:[1,0,0] neg_hi:[1,0,0]
	v_pk_fma_f32 v[76:77], v[112:113], v[38:39], v[106:107] op_sel:[0,1,0] neg_lo:[1,0,0] neg_hi:[1,0,0]
	v_pk_mul_f32 v[114:115], v[74:75], v[26:27] op_sel_hi:[1,0]
	v_pk_fma_f32 v[78:79], v[112:113], v[40:41], v[108:109] op_sel_hi:[1,0,1] neg_lo:[1,0,0] neg_hi:[1,0,0]
	v_pk_fma_f32 v[114:115], v[76:77], v[26:27], v[114:115] op_sel:[0,1,0]
	v_pk_fma_f32 v[80:81], v[112:113], v[40:41], v[110:111] op_sel:[0,1,0] neg_lo:[1,0,0] neg_hi:[1,0,0]
	v_pk_fma_f32 v[114:115], v[78:79], v[28:29], v[114:115] op_sel_hi:[1,0,1]
	v_pk_fma_f32 v[114:115], v[80:81], v[28:29], v[114:115] op_sel:[0,1,0]
	ds_write_b64 v96, v[114:115]
	s_waitcnt lgkmcnt(1)
	ds_read_b128 v[26:29], v0 offset:512
	ds_read_b128 v[30:33], v0 offset:4608
	ds_read_b128 v[34:37], v0 offset:8704
	ds_read_b128 v[42:45], v0 offset:16896
	ds_read_b128 v[38:41], v0 offset:20992
	ds_read_b64 v[82:83], v95 offset:12800
	v_pk_mul_f32 v[112:113], v[74:75], v[62:63] op_sel_hi:[1,0]
	v_pk_mul_f32 v[104:105], v[84:85], v[54:55] op_sel_hi:[1,0]
	v_pk_fma_f32 v[112:113], v[76:77], v[62:63], v[112:113] op_sel:[0,1,0]
	v_pk_mul_f32 v[106:107], v[84:85], v[54:55] op_sel:[0,1]
	v_pk_fma_f32 v[112:113], v[78:79], v[64:65], v[112:113] op_sel_hi:[1,0,1]
	v_pk_mul_f32 v[108:109], v[84:85], v[56:57] op_sel_hi:[1,0]
	v_pk_fma_f32 v[112:113], v[80:81], v[64:65], v[112:113] op_sel:[0,1,0]
	v_pk_mul_f32 v[110:111], v[84:85], v[56:57] op_sel:[0,1]
	v_pk_fma_f32 v[104:105], v[74:75], v[50:51], v[104:105] op_sel_hi:[1,0,1]
	v_add_f32_dpp v112, v112, v112 quad_perm:[1,0,3,2] row_mask:0xf bank_mask:0xf bound_ctrl:1
	v_add_f32_dpp v113, v113, v113 quad_perm:[1,0,3,2] row_mask:0xf bank_mask:0xf bound_ctrl:1
	v_pk_fma_f32 v[106:107], v[76:77], v[50:51], v[106:107] op_sel:[0,1,0]
	v_add_f32_dpp v112, v112, v112 quad_perm:[2,3,0,1] row_mask:0xf bank_mask:0xf bound_ctrl:1
	v_add_f32_dpp v113, v113, v113 quad_perm:[2,3,0,1] row_mask:0xf bank_mask:0xf bound_ctrl:1
	v_pk_fma_f32 v[108:109], v[78:79], v[52:53], v[108:109] op_sel_hi:[1,0,1]
	v_add_f32_dpp v112, v112, v112 row_half_mirror row_mask:0xf bank_mask:0xf bound_ctrl:1
	v_add_f32_dpp v113, v113, v113 row_half_mirror row_mask:0xf bank_mask:0xf bound_ctrl:1
	v_pk_fma_f32 v[110:111], v[80:81], v[52:53], v[110:111] op_sel:[0,1,0]
	v_add_f32_dpp v112, v112, v112 row_mirror row_mask:0xf bank_mask:0xf bound_ctrl:1
	v_add_f32_dpp v113, v113, v113 row_mirror row_mask:0xf bank_mask:0xf bound_ctrl:1
	v_pk_fma_f32 v[74:75], v[112:113], v[58:59], v[104:105] op_sel_hi:[1,0,1] neg_lo:[1,0,0] neg_hi:[1,0,0]
	v_pk_fma_f32 v[76:77], v[112:113], v[58:59], v[106:107] op_sel:[0,1,0] neg_lo:[1,0,0] neg_hi:[1,0,0]
	v_pk_mul_f32 v[114:115], v[74:75], v[46:47] op_sel_hi:[1,0]
	v_pk_fma_f32 v[78:79], v[112:113], v[60:61], v[108:109] op_sel_hi:[1,0,1] neg_lo:[1,0,0] neg_hi:[1,0,0]
	v_pk_fma_f32 v[114:115], v[76:77], v[46:47], v[114:115] op_sel:[0,1,0]
	v_pk_fma_f32 v[80:81], v[112:113], v[60:61], v[110:111] op_sel:[0,1,0] neg_lo:[1,0,0] neg_hi:[1,0,0]
	v_pk_fma_f32 v[114:115], v[78:79], v[48:49], v[114:115] op_sel_hi:[1,0,1]
	v_pk_fma_f32 v[114:115], v[80:81], v[48:49], v[114:115] op_sel:[0,1,0]
	ds_write_b64 v96, v[114:115] offset:2176
	s_waitcnt lgkmcnt(1)
; #define LAS __attribute__((address_space(3)))
; __device__ __forceinline__ void scan_job(LAS unsigned char* lds, const AP a, int l, int bl, int hd, int rh) {
;     ...
;             for (int st = 0; st < CH; ++st) {
;                 const f32x4 w = wN, kk = kkN, b = bN, k = kN, r = rN; const f32x2 v = vN;
;                 const int on = ((st + 1) & (CH - 1)) * 64;
;                 rN = *(const LAS f32x4*)(bp + on + o0); wN = *(const LAS f32x4*)(bp + VSZ + on + o0); kN = *(const LAS f32x4*)(bp + 2 * VSZ + on + o0); kkN = *(const LAS f32x4*)(bp + 4 * VSZ + on + o0); bN = *(const LAS f32x4*)(bp + 5 * VSZ + on + o0);
;                 vN = *(const LAS f32x2*)(bp + on + vo);
;                 const f32x2 kk0 = {kk.x, kk.y}, kk1 = {kk.z, kk.w}, w0 = {w.x, w.y}, w1 = {w.z, w.w}, b0 = {b.x, b.y}, b1 = {b.z, b.w}, k0 = {k.x, k.y}, k1 = {k.z, k.w}, r0 = {r.x, r.y}, r1 = {r.z, r.w};
;                 const f32x2 va = {v.x, v.x}, vb = {v.y, v.y};
;                 const f32x2 pa = sA0 * kk0 + sA1 * kk1, pb = sB0 * kk0 + sB1 * kk1;
;                 const float saA = -red16(pa.x + pa.y), saB = -red16(pb.x + pb.y);
;                 const f32x2 sav = {saA, saA}, sbv = {saB, saB};
;                 sA0 = sA0 * w0 + (sav * b0 + va * k0); sA1 = sA1 * w1 + (sav * b1 + va * k1);
;                 sB0 = sB0 * w0 + (sbv * b0 + vb * k0); sB1 = sB1 * w1 + (sbv * b1 + vb * k1);
;                 const f32x2 ya = sA0 * r0 + sA1 * r1, yb = sB0 * r0 + sB1 * r1;
;                 *(LAS f32x2*)(yl + st * 16 * YSTR) = (f32x2){ya.x + ya.y, yb.x + yb.y};
;             }
	ds_read_b128 v[46:49], v0 offset:768
	ds_read_b128 v[50:53], v0 offset:4864
	ds_read_b128 v[54:57], v0 offset:8960
	ds_read_b128 v[62:65], v0 offset:17152
	ds_read_b128 v[58:61], v0 offset:21248
	ds_read_b64 v[84:85], v95 offset:13056
	v_pk_mul_f32 v[112:113], v[74:75], v[42:43] op_sel_hi:[1,0]
	v_pk_mul_f32 v[104:105], v[82:83], v[34:35] op_sel_hi:[1,0]
	v_pk_fma_f32 v[112:113], v[76:77], v[42:43], v[112:113] op_sel:[0,1,0]
	v_pk_mul_f32 v[106:107], v[82:83], v[34:35] op_sel:[0,1]
	v_pk_fma_f32 v[112:113], v[78:79], v[44:45], v[112:113] op_sel_hi:[1,0,1]
	v_pk_mul_f32 v[108:109], v[82:83], v[36:37] op_sel_hi:[1,0]
	v_pk_fma_f32 v[112:113], v[80:81], v[44:45], v[112:113] op_sel:[0,1,0]
	v_pk_mul_f32 v[110:111], v[82:83], v[36:37] op_sel:[0,1]
	v_pk_fma_f32 v[104:105], v[74:75], v[30:31], v[104:105] op_sel_hi:[1,0,1]
	v_add_f32_dpp v112, v112, v112 quad_perm:[1,0,3,2] row_mask:0xf bank_mask:0xf bound_ctrl:1
	v_add_f32_dpp v113, v113, v113 quad_perm:[1,0,3,2] row_mask:0xf bank_mask:0xf bound_ctrl:1
	v_pk_fma_f32 v[106:107], v[76:77], v[30:31], v[106:107] op_sel:[0,1,0]
	v_add_f32_dpp v112, v112, v112 quad_perm:[2,3,0,1] row_mask:0xf bank_mask:0xf bound_ctrl:1
	v_add_f32_dpp v113, v113, v113 quad_perm:[2,3,0,1] row_mask:0xf bank_mask:0xf bound_ctrl:1
	v_pk_fma_f32 v[108:109], v[78:79], v[32:33], v[108:109] op_sel_hi:[1,0,1]
	v_add_f32_dpp v112, v112, v112 row_half_mirror row_mask:0xf bank_mask:0xf bound_ctrl:1
	v_add_f32_dpp v113, v113, v113 row_half_mirror row_mask:0xf bank_mask:0xf bound_ctrl:1
	v_pk_fma_f32 v[110:111], v[80:81], v[32:33], v[110:111] op_sel:[0,1,0]
	v_add_f32_dpp v112, v112, v112 row_mirror row_mask:0xf bank_mask:0xf bound_ctrl:1
	v_add_f32_dpp v113, v113, v113 row_mirror row_mask:0xf bank_mask:0xf bound_ctrl:1
	v_pk_fma_f32 v[74:75], v[112:113], v[38:39], v[104:105] op_sel_hi:[1,0,1] neg_lo:[1,0,0] neg_hi:[1,0,0]
	v_pk_fma_f32 v[76:77], v[112:113], v[38:39], v[106:107] op_sel:[0,1,0] neg_lo:[1,0,0] neg_hi:[1,0,0]
	v_pk_mul_f32 v[114:115], v[74:75], v[26:27] op_sel_hi:[1,0]
	v_pk_fma_f32 v[78:79], v[112:113], v[40:41], v[108:109] op_sel_hi:[1,0,1] neg_lo:[1,0,0] neg_hi:[1,0,0]
	v_pk_fma_f32 v[114:115], v[76:77], v[26:27], v[114:115] op_sel:[0,1,0]
	v_pk_fma_f32 v[80:81], v[112:113], v[40:41], v[110:111] op_sel:[0,1,0] neg_lo:[1,0,0] neg_hi:[1,0,0]
	v_pk_fma_f32 v[114:115], v[78:79], v[28:29], v[114:115] op_sel_hi:[1,0,1]
	v_pk_fma_f32 v[114:115], v[80:81], v[28:29], v[114:115] op_sel:[0,1,0]
	ds_write_b64 v96, v[114:115] offset:4352
	s_waitcnt lgkmcnt(1)
	ds_read_b128 v[26:29], v0 offset:1024
	ds_read_b128 v[30:33], v0 offset:5120
	ds_read_b128 v[34:37], v0 offset:9216
	ds_read_b128 v[42:45], v0 offset:17408
	ds_read_b128 v[38:41], v0 offset:21504
	ds_read_b64 v[82:83], v95 offset:13312
	v_pk_mul_f32 v[112:113], v[74:75], v[62:63] op_sel_hi:[1,0]
	v_pk_mul_f32 v[104:105], v[84:85], v[54:55] op_sel_hi:[1,0]
	v_pk_fma_f32 v[112:113], v[76:77], v[62:63], v[112:113] op_sel:[0,1,0]
	v_pk_mul_f32 v[106:107], v[84:85], v[54:55] op_sel:[0,1]
	v_pk_fma_f32 v[112:113], v[78:79], v[64:65], v[112:113] op_sel_hi:[1,0,1]
	v_pk_mul_f32 v[108:109], v[84:85], v[56:57] op_sel_hi:[1,0]
	v_pk_fma_f32 v[112:113], v[80:81], v[64:65], v[112:113] op_sel:[0,1,0]
	v_pk_mul_f32 v[110:111], v[84:85], v[56:57] op_sel:[0,1]
	v_pk_fma_f32 v[104:105], v[74:75], v[50:51], v[104:105] op_sel_hi:[1,0,1]
	v_add_f32_dpp v112, v112, v112 quad_perm:[1,0,3,2] row_mask:0xf bank_mask:0xf bound_ctrl:1
	v_add_f32_dpp v113, v113, v113 quad_perm:[1,0,3,2] row_mask:0xf bank_mask:0xf bound_ctrl:1
	v_pk_fma_f32 v[106:107], v[76:77], v[50:51], v[106:107] op_sel:[0,1,0]
	v_add_f32_dpp v112, v112, v112 quad_perm:[2,3,0,1] row_mask:0xf bank_mask:0xf bound_ctrl:1
	v_add_f32_dpp v113, v113, v113 quad_perm:[2,3,0,1] row_mask:0xf bank_mask:0xf bound_ctrl:1
	v_pk_fma_f32 v[108:109], v[78:79], v[52:53], v[108:109] op_sel_hi:[1,0,1]
	v_add_f32_dpp v112, v112, v112 row_half_mirror row_mask:0xf bank_mask:0xf bound_ctrl:1
	v_add_f32_dpp v113, v113, v113 row_half_mirror row_mask:0xf bank_mask:0xf bound_ctrl:1
	v_pk_fma_f32 v[110:111], v[80:81], v[52:53], v[110:111] op_sel:[0,1,0]
	v_add_f32_dpp v112, v112, v112 row_mirror row_mask:0xf bank_mask:0xf bound_ctrl:1
	v_add_f32_dpp v113, v113, v113 row_mirror row_mask:0xf bank_mask:0xf bound_ctrl:1
	v_pk_fma_f32 v[74:75], v[112:113], v[58:59], v[104:105] op_sel_hi:[1,0,1] neg_lo:[1,0,0] neg_hi:[1,0,0]
	v_pk_fma_f32 v[76:77], v[112:113], v[58:59], v[106:107] op_sel:[0,1,0] neg_lo:[1,0,0] neg_hi:[1,0,0]
	v_pk_mul_f32 v[114:115], v[74:75], v[46:47] op_sel_hi:[1,0]
	v_pk_fma_f32 v[78:79], v[112:113], v[60:61], v[108:109] op_sel_hi:[1,0,1] neg_lo:[1,0,0] neg_hi:[1,0,0]
	v_pk_fma_f32 v[114:115], v[76:77], v[46:47], v[114:115] op_sel:[0,1,0]
	v_pk_fma_f32 v[80:81], v[112:113], v[60:61], v[110:111] op_sel:[0,1,0] neg_lo:[1,0,0] neg_hi:[1,0,0]
	v_pk_fma_f32 v[114:115], v[78:79], v[48:49], v[114:115] op_sel_hi:[1,0,1]
	v_pk_fma_f32 v[114:115], v[80:81], v[48:49], v[114:115] op_sel:[0,1,0]
	ds_write_b64 v96, v[114:115] offset:6528
	s_waitcnt lgkmcnt(1)
; #define LAS __attribute__((address_space(3)))
; __device__ __forceinline__ void scan_job(LAS unsigned char* lds, const AP a, int l, int bl, int hd, int rh) {
;     ...
;             for (int st = 0; st < CH; ++st) {
;                 const f32x4 w = wN, kk = kkN, b = bN, k = kN, r = rN; const f32x2 v = vN;
;                 const int on = ((st + 1) & (CH - 1)) * 64;
;                 rN = *(const LAS f32x4*)(bp + on + o0); wN = *(const LAS f32x4*)(bp + VSZ + on + o0); kN = *(const LAS f32x4*)(bp + 2 * VSZ + on + o0); kkN = *(const LAS f32x4*)(bp + 4 * VSZ + on + o0); bN = *(const LAS f32x4*)(bp + 5 * VSZ + on + o0);
;                 vN = *(const LAS f32x2*)(bp + on + vo);
;                 const f32x2 kk0 = {kk.x, kk.y}, kk1 = {kk.z, kk.w}, w0 = {w.x, w.y}, w1 = {w.z, w.w}, b0 = {b.x, b.y}, b1 = {b.z, b.w}, k0 = {k.x, k.y}, k1 = {k.z, k.w}, r0 = {r.x, r.y}, r1 = {r.z, r.w};
;                 const f32x2 va = {v.x, v.x}, vb = {v.y, v.y};
;                 const f32x2 pa = sA0 * kk0 + sA1 * kk1, pb = sB0 * kk0 + sB1 * kk1;
;                 const float saA = -red16(pa.x + pa.y), saB = -red16(pb.x + pb.y);
;                 const f32x2 sav = {saA, saA}, sbv = {saB, saB};
;                 sA0 = sA0 * w0 + (sav * b0 + va * k0); sA1 = sA1 * w1 + (sav * b1 + va * k1);
;                 sB0 = sB0 * w0 + (sbv * b0 + vb * k0); sB1 = sB1 * w1 + (sbv * b1 + vb * k1);
;                 const f32x2 ya = sA0 * r0 + sA1 * r1, yb = sB0 * r0 + sB1 * r1;
;                 *(LAS f32x2*)(yl + st * 16 * YSTR) = (f32x2){ya.x + ya.y, yb.x + yb.y};
;             }
	ds_read_b128 v[46:49], v0 offset:1280
	ds_read_b128 v[50:53], v0 offset:5376
	ds_read_b128 v[54:57], v0 offset:9472
	ds_read_b128 v[62:65], v0 offset:17664
	ds_read_b128 v[58:61], v0 offset:21760
	ds_read_b64 v[84:85], v95 offset:13568
	v_pk_mul_f32 v[112:113], v[74:75], v[42:43] op_sel_hi:[1,0]
	v_pk_mul_f32 v[104:105], v[82:83], v[34:35] op_sel_hi:[1,0]
	v_pk_fma_f32 v[112:113], v[76:77], v[42:43], v[112:113] op_sel:[0,1,0]
	v_pk_mul_f32 v[106:107], v[82:83], v[34:35] op_sel:[0,1]
	v_pk_fma_f32 v[112:113], v[78:79], v[44:45], v[112:113] op_sel_hi:[1,0,1]
	v_pk_mul_f32 v[108:109], v[82:83], v[36:37] op_sel_hi:[1,0]
	v_pk_fma_f32 v[112:113], v[80:81], v[44:45], v[112:113] op_sel:[0,1,0]
	v_pk_mul_f32 v[110:111], v[82:83], v[36:37] op_sel:[0,1]
	v_pk_fma_f32 v[104:105], v[74:75], v[30:31], v[104:105] op_sel_hi:[1,0,1]
	v_add_f32_dpp v112, v112, v112 quad_perm:[1,0,3,2] row_mask:0xf bank_mask:0xf bound_ctrl:1
	v_add_f32_dpp v113, v113, v113 quad_perm:[1,0,3,2] row_mask:0xf bank_mask:0xf bound_ctrl:1
	v_pk_fma_f32 v[106:107], v[76:77], v[30:31], v[106:107] op_sel:[0,1,0]
	v_add_f32_dpp v112, v112, v112 quad_perm:[2,3,0,1] row_mask:0xf bank_mask:0xf bound_ctrl:1
	v_add_f32_dpp v113, v113, v113 quad_perm:[2,3,0,1] row_mask:0xf bank_mask:0xf bound_ctrl:1
	v_pk_fma_f32 v[108:109], v[78:79], v[32:33], v[108:109] op_sel_hi:[1,0,1]
	v_add_f32_dpp v112, v112, v112 row_half_mirror row_mask:0xf bank_mask:0xf bound_ctrl:1
	v_add_f32_dpp v113, v113, v113 row_half_mirror row_mask:0xf bank_mask:0xf bound_ctrl:1
	v_pk_fma_f32 v[110:111], v[80:81], v[32:33], v[110:111] op_sel:[0,1,0]
	v_add_f32_dpp v112, v112, v112 row_mirror row_mask:0xf bank_mask:0xf bound_ctrl:1
	v_add_f32_dpp v113, v113, v113 row_mirror row_mask:0xf bank_mask:0xf bound_ctrl:1
	v_pk_fma_f32 v[74:75], v[112:113], v[38:39], v[104:105] op_sel_hi:[1,0,1] neg_lo:[1,0,0] neg_hi:[1,0,0]
	v_pk_fma_f32 v[76:77], v[112:113], v[38:39], v[106:107] op_sel:[0,1,0] neg_lo:[1,0,0] neg_hi:[1,0,0]
	v_pk_mul_f32 v[114:115], v[74:75], v[26:27] op_sel_hi:[1,0]
	v_pk_fma_f32 v[78:79], v[112:113], v[40:41], v[108:109] op_sel_hi:[1,0,1] neg_lo:[1,0,0] neg_hi:[1,0,0]
	v_pk_fma_f32 v[114:115], v[76:77], v[26:27], v[114:115] op_sel:[0,1,0]
	v_pk_fma_f32 v[80:81], v[112:113], v[40:41], v[110:111] op_sel:[0,1,0] neg_lo:[1,0,0] neg_hi:[1,0,0]
	v_pk_fma_f32 v[114:115], v[78:79], v[28:29], v[114:115] op_sel_hi:[1,0,1]
	v_pk_fma_f32 v[114:115], v[80:81], v[28:29], v[114:115] op_sel:[0,1,0]
	ds_write_b64 v96, v[114:115] offset:8704
	s_waitcnt lgkmcnt(1)
	ds_read_b128 v[26:29], v0 offset:1536
	ds_read_b128 v[30:33], v0 offset:5632
	ds_read_b128 v[34:37], v0 offset:9728
	ds_read_b128 v[42:45], v0 offset:17920
	ds_read_b128 v[38:41], v0 offset:22016
	ds_read_b64 v[82:83], v95 offset:13824
	v_pk_mul_f32 v[112:113], v[74:75], v[62:63] op_sel_hi:[1,0]
	v_pk_mul_f32 v[104:105], v[84:85], v[54:55] op_sel_hi:[1,0]
	v_pk_fma_f32 v[112:113], v[76:77], v[62:63], v[112:113] op_sel:[0,1,0]
	v_pk_mul_f32 v[106:107], v[84:85], v[54:55] op_sel:[0,1]
	v_pk_fma_f32 v[112:113], v[78:79], v[64:65], v[112:113] op_sel_hi:[1,0,1]
	v_pk_mul_f32 v[108:109], v[84:85], v[56:57] op_sel_hi:[1,0]
	v_pk_fma_f32 v[112:113], v[80:81], v[64:65], v[112:113] op_sel:[0,1,0]
	v_pk_mul_f32 v[110:111], v[84:85], v[56:57] op_sel:[0,1]
	v_pk_fma_f32 v[104:105], v[74:75], v[50:51], v[104:105] op_sel_hi:[1,0,1]
	v_add_f32_dpp v112, v112, v112 quad_perm:[1,0,3,2] row_mask:0xf bank_mask:0xf bound_ctrl:1
	v_add_f32_dpp v113, v113, v113 quad_perm:[1,0,3,2] row_mask:0xf bank_mask:0xf bound_ctrl:1
	v_pk_fma_f32 v[106:107], v[76:77], v[50:51], v[106:107] op_sel:[0,1,0]
	v_add_f32_dpp v112, v112, v112 quad_perm:[2,3,0,1] row_mask:0xf bank_mask:0xf bound_ctrl:1
	v_add_f32_dpp v113, v113, v113 quad_perm:[2,3,0,1] row_mask:0xf bank_mask:0xf bound_ctrl:1
	v_pk_fma_f32 v[108:109], v[78:79], v[52:53], v[108:109] op_sel_hi:[1,0,1]
	v_add_f32_dpp v112, v112, v112 row_half_mirror row_mask:0xf bank_mask:0xf bound_ctrl:1
	v_add_f32_dpp v113, v113, v113 row_half_mirror row_mask:0xf bank_mask:0xf bound_ctrl:1
	v_pk_fma_f32 v[110:111], v[80:81], v[52:53], v[110:111] op_sel:[0,1,0]
	v_add_f32_dpp v112, v112, v112 row_mirror row_mask:0xf bank_mask:0xf bound_ctrl:1
	v_add_f32_dpp v113, v113, v113 row_mirror row_mask:0xf bank_mask:0xf bound_ctrl:1
	v_pk_fma_f32 v[74:75], v[112:113], v[58:59], v[104:105] op_sel_hi:[1,0,1] neg_lo:[1,0,0] neg_hi:[1,0,0]
	v_pk_fma_f32 v[76:77], v[112:113], v[58:59], v[106:107] op_sel:[0,1,0] neg_lo:[1,0,0] neg_hi:[1,0,0]
	v_pk_mul_f32 v[114:115], v[74:75], v[46:47] op_sel_hi:[1,0]
	v_pk_fma_f32 v[78:79], v[112:113], v[60:61], v[108:109] op_sel_hi:[1,0,1] neg_lo:[1,0,0] neg_hi:[1,0,0]
	v_pk_fma_f32 v[114:115], v[76:77], v[46:47], v[114:115] op_sel:[0,1,0]
	v_pk_fma_f32 v[80:81], v[112:113], v[60:61], v[110:111] op_sel:[0,1,0] neg_lo:[1,0,0] neg_hi:[1,0,0]
	v_pk_fma_f32 v[114:115], v[78:79], v[48:49], v[114:115] op_sel_hi:[1,0,1]
	v_pk_fma_f32 v[114:115], v[80:81], v[48:49], v[114:115] op_sel:[0,1,0]
	ds_write_b64 v96, v[114:115] offset:10880
	s_waitcnt lgkmcnt(1)
; #define LAS __attribute__((address_space(3)))
; __device__ __forceinline__ void scan_job(LAS unsigned char* lds, const AP a, int l, int bl, int hd, int rh) {
;     ...
;             for (int st = 0; st < CH; ++st) {
;                 const f32x4 w = wN, kk = kkN, b = bN, k = kN, r = rN; const f32x2 v = vN;
;                 const int on = ((st + 1) & (CH - 1)) * 64;
;                 rN = *(const LAS f32x4*)(bp + on + o0); wN = *(const LAS f32x4*)(bp + VSZ + on + o0); kN = *(const LAS f32x4*)(bp + 2 * VSZ + on + o0); kkN = *(const LAS f32x4*)(bp + 4 * VSZ + on + o0); bN = *(const LAS f32x4*)(bp + 5 * VSZ + on + o0);
;                 vN = *(const LAS f32x2*)(bp + on + vo);
;                 const f32x2 kk0 = {kk.x, kk.y}, kk1 = {kk.z, kk.w}, w0 = {w.x, w.y}, w1 = {w.z, w.w}, b0 = {b.x, b.y}, b1 = {b.z, b.w}, k0 = {k.x, k.y}, k1 = {k.z, k.w}, r0 = {r.x, r.y}, r1 = {r.z, r.w};
;                 const f32x2 va = {v.x, v.x}, vb = {v.y, v.y};
;                 const f32x2 pa = sA0 * kk0 + sA1 * kk1, pb = sB0 * kk0 + sB1 * kk1;
;                 const float saA = -red16(pa.x + pa.y), saB = -red16(pb.x + pb.y);
;                 const f32x2 sav = {saA, saA}, sbv = {saB, saB};
;                 sA0 = sA0 * w0 + (sav * b0 + va * k0); sA1 = sA1 * w1 + (sav * b1 + va * k1);
;                 sB0 = sB0 * w0 + (sbv * b0 + vb * k0); sB1 = sB1 * w1 + (sbv * b1 + vb * k1);
;                 const f32x2 ya = sA0 * r0 + sA1 * r1, yb = sB0 * r0 + sB1 * r1;
;                 *(LAS f32x2*)(yl + st * 16 * YSTR) = (f32x2){ya.x + ya.y, yb.x + yb.y};
;             }
	ds_read_b128 v[46:49], v0 offset:1792
	ds_read_b128 v[50:53], v0 offset:5888
	ds_read_b128 v[54:57], v0 offset:9984
	ds_read_b128 v[62:65], v0 offset:18176
	ds_read_b128 v[58:61], v0 offset:22272
	ds_read_b64 v[84:85], v95 offset:14080
	v_pk_mul_f32 v[112:113], v[74:75], v[42:43] op_sel_hi:[1,0]
	v_pk_mul_f32 v[104:105], v[82:83], v[34:35] op_sel_hi:[1,0]
	v_pk_fma_f32 v[112:113], v[76:77], v[42:43], v[112:113] op_sel:[0,1,0]
	v_pk_mul_f32 v[106:107], v[82:83], v[34:35] op_sel:[0,1]
	v_pk_fma_f32 v[112:113], v[78:79], v[44:45], v[112:113] op_sel_hi:[1,0,1]
	v_pk_mul_f32 v[108:109], v[82:83], v[36:37] op_sel_hi:[1,0]
	v_pk_fma_f32 v[112:113], v[80:81], v[44:45], v[112:113] op_sel:[0,1,0]
	v_pk_mul_f32 v[110:111], v[82:83], v[36:37] op_sel:[0,1]
	v_pk_fma_f32 v[104:105], v[74:75], v[30:31], v[104:105] op_sel_hi:[1,0,1]
	v_add_f32_dpp v112, v112, v112 quad_perm:[1,0,3,2] row_mask:0xf bank_mask:0xf bound_ctrl:1
	v_add_f32_dpp v113, v113, v113 quad_perm:[1,0,3,2] row_mask:0xf bank_mask:0xf bound_ctrl:1
	v_pk_fma_f32 v[106:107], v[76:77], v[30:31], v[106:107] op_sel:[0,1,0]
	v_add_f32_dpp v112, v112, v112 quad_perm:[2,3,0,1] row_mask:0xf bank_mask:0xf bound_ctrl:1
	v_add_f32_dpp v113, v113, v113 quad_perm:[2,3,0,1] row_mask:0xf bank_mask:0xf bound_ctrl:1
	v_pk_fma_f32 v[108:109], v[78:79], v[32:33], v[108:109] op_sel_hi:[1,0,1]
	v_add_f32_dpp v112, v112, v112 row_half_mirror row_mask:0xf bank_mask:0xf bound_ctrl:1
	v_add_f32_dpp v113, v113, v113 row_half_mirror row_mask:0xf bank_mask:0xf bound_ctrl:1
	v_pk_fma_f32 v[110:111], v[80:81], v[32:33], v[110:111] op_sel:[0,1,0]
	v_add_f32_dpp v112, v112, v112 row_mirror row_mask:0xf bank_mask:0xf bound_ctrl:1
	v_add_f32_dpp v113, v113, v113 row_mirror row_mask:0xf bank_mask:0xf bound_ctrl:1
	v_pk_fma_f32 v[74:75], v[112:113], v[38:39], v[104:105] op_sel_hi:[1,0,1] neg_lo:[1,0,0] neg_hi:[1,0,0]
	v_pk_fma_f32 v[76:77], v[112:113], v[38:39], v[106:107] op_sel:[0,1,0] neg_lo:[1,0,0] neg_hi:[1,0,0]
	v_pk_mul_f32 v[114:115], v[74:75], v[26:27] op_sel_hi:[1,0]
	v_pk_fma_f32 v[78:79], v[112:113], v[40:41], v[108:109] op_sel_hi:[1,0,1] neg_lo:[1,0,0] neg_hi:[1,0,0]
	v_pk_fma_f32 v[114:115], v[76:77], v[26:27], v[114:115] op_sel:[0,1,0]
	v_pk_fma_f32 v[80:81], v[112:113], v[40:41], v[110:111] op_sel:[0,1,0] neg_lo:[1,0,0] neg_hi:[1,0,0]
	v_pk_fma_f32 v[114:115], v[78:79], v[28:29], v[114:115] op_sel_hi:[1,0,1]
	v_pk_fma_f32 v[114:115], v[80:81], v[28:29], v[114:115] op_sel:[0,1,0]
	ds_write_b64 v96, v[114:115] offset:13056
	s_waitcnt lgkmcnt(1)
	ds_read_b128 v[26:29], v0 offset:2048
	ds_read_b128 v[30:33], v0 offset:6144
	ds_read_b128 v[34:37], v0 offset:10240
	ds_read_b128 v[42:45], v0 offset:18432
	ds_read_b128 v[38:41], v0 offset:22528
	ds_read_b64 v[82:83], v95 offset:14336
	v_pk_mul_f32 v[112:113], v[74:75], v[62:63] op_sel_hi:[1,0]
	v_pk_mul_f32 v[104:105], v[84:85], v[54:55] op_sel_hi:[1,0]
	v_pk_fma_f32 v[112:113], v[76:77], v[62:63], v[112:113] op_sel:[0,1,0]
	v_pk_mul_f32 v[106:107], v[84:85], v[54:55] op_sel:[0,1]
	v_pk_fma_f32 v[112:113], v[78:79], v[64:65], v[112:113] op_sel_hi:[1,0,1]
	v_pk_mul_f32 v[108:109], v[84:85], v[56:57] op_sel_hi:[1,0]
	v_pk_fma_f32 v[112:113], v[80:81], v[64:65], v[112:113] op_sel:[0,1,0]
	v_pk_mul_f32 v[110:111], v[84:85], v[56:57] op_sel:[0,1]
	v_pk_fma_f32 v[104:105], v[74:75], v[50:51], v[104:105] op_sel_hi:[1,0,1]
	v_add_f32_dpp v112, v112, v112 quad_perm:[1,0,3,2] row_mask:0xf bank_mask:0xf bound_ctrl:1
	v_add_f32_dpp v113, v113, v113 quad_perm:[1,0,3,2] row_mask:0xf bank_mask:0xf bound_ctrl:1
	v_pk_fma_f32 v[106:107], v[76:77], v[50:51], v[106:107] op_sel:[0,1,0]
	v_add_f32_dpp v112, v112, v112 quad_perm:[2,3,0,1] row_mask:0xf bank_mask:0xf bound_ctrl:1
	v_add_f32_dpp v113, v113, v113 quad_perm:[2,3,0,1] row_mask:0xf bank_mask:0xf bound_ctrl:1
	v_pk_fma_f32 v[108:109], v[78:79], v[52:53], v[108:109] op_sel_hi:[1,0,1]
	v_add_f32_dpp v112, v112, v112 row_half_mirror row_mask:0xf bank_mask:0xf bound_ctrl:1
	v_add_f32_dpp v113, v113, v113 row_half_mirror row_mask:0xf bank_mask:0xf bound_ctrl:1
	v_pk_fma_f32 v[110:111], v[80:81], v[52:53], v[110:111] op_sel:[0,1,0]
	v_add_f32_dpp v112, v112, v112 row_mirror row_mask:0xf bank_mask:0xf bound_ctrl:1
	v_add_f32_dpp v113, v113, v113 row_mirror row_mask:0xf bank_mask:0xf bound_ctrl:1
	v_pk_fma_f32 v[74:75], v[112:113], v[58:59], v[104:105] op_sel_hi:[1,0,1] neg_lo:[1,0,0] neg_hi:[1,0,0]
	v_pk_fma_f32 v[76:77], v[112:113], v[58:59], v[106:107] op_sel:[0,1,0] neg_lo:[1,0,0] neg_hi:[1,0,0]
	v_pk_mul_f32 v[114:115], v[74:75], v[46:47] op_sel_hi:[1,0]
	v_pk_fma_f32 v[78:79], v[112:113], v[60:61], v[108:109] op_sel_hi:[1,0,1] neg_lo:[1,0,0] neg_hi:[1,0,0]
	v_pk_fma_f32 v[114:115], v[76:77], v[46:47], v[114:115] op_sel:[0,1,0]
	v_pk_fma_f32 v[80:81], v[112:113], v[60:61], v[110:111] op_sel:[0,1,0] neg_lo:[1,0,0] neg_hi:[1,0,0]
	v_pk_fma_f32 v[114:115], v[78:79], v[48:49], v[114:115] op_sel_hi:[1,0,1]
	v_pk_fma_f32 v[114:115], v[80:81], v[48:49], v[114:115] op_sel:[0,1,0]
	ds_write_b64 v96, v[114:115] offset:15232
	s_waitcnt lgkmcnt(1)
; #define LAS __attribute__((address_space(3)))
; __device__ __forceinline__ void scan_job(LAS unsigned char* lds, const AP a, int l, int bl, int hd, int rh) {
;     ...
;             for (int st = 0; st < CH; ++st) {
;                 const f32x4 w = wN, kk = kkN, b = bN, k = kN, r = rN; const f32x2 v = vN;
;                 const int on = ((st + 1) & (CH - 1)) * 64;
;                 rN = *(const LAS f32x4*)(bp + on + o0); wN = *(const LAS f32x4*)(bp + VSZ + on + o0); kN = *(const LAS f32x4*)(bp + 2 * VSZ + on + o0); kkN = *(const LAS f32x4*)(bp + 4 * VSZ + on + o0); bN = *(const LAS f32x4*)(bp + 5 * VSZ + on + o0);
;                 vN = *(const LAS f32x2*)(bp + on + vo);
;                 const f32x2 kk0 = {kk.x, kk.y}, kk1 = {kk.z, kk.w}, w0 = {w.x, w.y}, w1 = {w.z, w.w}, b0 = {b.x, b.y}, b1 = {b.z, b.w}, k0 = {k.x, k.y}, k1 = {k.z, k.w}, r0 = {r.x, r.y}, r1 = {r.z, r.w};
;                 const f32x2 va = {v.x, v.x}, vb = {v.y, v.y};
;                 const f32x2 pa = sA0 * kk0 + sA1 * kk1, pb = sB0 * kk0 + sB1 * kk1;
;                 const float saA = -red16(pa.x + pa.y), saB = -red16(pb.x + pb.y);
;                 const f32x2 sav = {saA, saA}, sbv = {saB, saB};
;                 sA0 = sA0 * w0 + (sav * b0 + va * k0); sA1 = sA1 * w1 + (sav * b1 + va * k1);
;                 sB0 = sB0 * w0 + (sbv * b0 + vb * k0); sB1 = sB1 * w1 + (sbv * b1 + vb * k1);
;                 const f32x2 ya = sA0 * r0 + sA1 * r1, yb = sB0 * r0 + sB1 * r1;
;                 *(LAS f32x2*)(yl + st * 16 * YSTR) = (f32x2){ya.x + ya.y, yb.x + yb.y};
;             }
	ds_read_b128 v[46:49], v0 offset:2304
	ds_read_b128 v[50:53], v0 offset:6400
	ds_read_b128 v[54:57], v0 offset:10496
	ds_read_b128 v[62:65], v0 offset:18688
	ds_read_b128 v[58:61], v0 offset:22784
	ds_read_b64 v[84:85], v95 offset:14592
	v_pk_mul_f32 v[112:113], v[74:75], v[42:43] op_sel_hi:[1,0]
	v_pk_mul_f32 v[104:105], v[82:83], v[34:35] op_sel_hi:[1,0]
	v_pk_fma_f32 v[112:113], v[76:77], v[42:43], v[112:113] op_sel:[0,1,0]
	v_pk_mul_f32 v[106:107], v[82:83], v[34:35] op_sel:[0,1]
	v_pk_fma_f32 v[112:113], v[78:79], v[44:45], v[112:113] op_sel_hi:[1,0,1]
	v_pk_mul_f32 v[108:109], v[82:83], v[36:37] op_sel_hi:[1,0]
	v_pk_fma_f32 v[112:113], v[80:81], v[44:45], v[112:113] op_sel:[0,1,0]
	v_pk_mul_f32 v[110:111], v[82:83], v[36:37] op_sel:[0,1]
	v_pk_fma_f32 v[104:105], v[74:75], v[30:31], v[104:105] op_sel_hi:[1,0,1]
	v_add_f32_dpp v112, v112, v112 quad_perm:[1,0,3,2] row_mask:0xf bank_mask:0xf bound_ctrl:1
	v_add_f32_dpp v113, v113, v113 quad_perm:[1,0,3,2] row_mask:0xf bank_mask:0xf bound_ctrl:1
	v_pk_fma_f32 v[106:107], v[76:77], v[30:31], v[106:107] op_sel:[0,1,0]
	v_add_f32_dpp v112, v112, v112 quad_perm:[2,3,0,1] row_mask:0xf bank_mask:0xf bound_ctrl:1
	v_add_f32_dpp v113, v113, v113 quad_perm:[2,3,0,1] row_mask:0xf bank_mask:0xf bound_ctrl:1
	v_pk_fma_f32 v[108:109], v[78:79], v[32:33], v[108:109] op_sel_hi:[1,0,1]
	v_add_f32_dpp v112, v112, v112 row_half_mirror row_mask:0xf bank_mask:0xf bound_ctrl:1
	v_add_f32_dpp v113, v113, v113 row_half_mirror row_mask:0xf bank_mask:0xf bound_ctrl:1
	v_pk_fma_f32 v[110:111], v[80:81], v[32:33], v[110:111] op_sel:[0,1,0]
	v_add_f32_dpp v112, v112, v112 row_mirror row_mask:0xf bank_mask:0xf bound_ctrl:1
	v_add_f32_dpp v113, v113, v113 row_mirror row_mask:0xf bank_mask:0xf bound_ctrl:1
	v_pk_fma_f32 v[74:75], v[112:113], v[38:39], v[104:105] op_sel_hi:[1,0,1] neg_lo:[1,0,0] neg_hi:[1,0,0]
	v_pk_fma_f32 v[76:77], v[112:113], v[38:39], v[106:107] op_sel:[0,1,0] neg_lo:[1,0,0] neg_hi:[1,0,0]
	v_pk_mul_f32 v[114:115], v[74:75], v[26:27] op_sel_hi:[1,0]
	v_pk_fma_f32 v[78:79], v[112:113], v[40:41], v[108:109] op_sel_hi:[1,0,1] neg_lo:[1,0,0] neg_hi:[1,0,0]
	v_pk_fma_f32 v[114:115], v[76:77], v[26:27], v[114:115] op_sel:[0,1,0]
	v_pk_fma_f32 v[80:81], v[112:113], v[40:41], v[110:111] op_sel:[0,1,0] neg_lo:[1,0,0] neg_hi:[1,0,0]
	v_pk_fma_f32 v[114:115], v[78:79], v[28:29], v[114:115] op_sel_hi:[1,0,1]
	v_pk_fma_f32 v[114:115], v[80:81], v[28:29], v[114:115] op_sel:[0,1,0]
	ds_write_b64 v96, v[114:115] offset:17408
	s_waitcnt lgkmcnt(1)
	ds_read_b128 v[26:29], v0 offset:2560
	ds_read_b128 v[30:33], v0 offset:6656
	ds_read_b128 v[34:37], v0 offset:10752
	ds_read_b128 v[42:45], v0 offset:18944
	ds_read_b128 v[38:41], v0 offset:23040
	ds_read_b64 v[82:83], v95 offset:14848
	v_pk_mul_f32 v[112:113], v[74:75], v[62:63] op_sel_hi:[1,0]
	v_pk_mul_f32 v[104:105], v[84:85], v[54:55] op_sel_hi:[1,0]
	v_pk_fma_f32 v[112:113], v[76:77], v[62:63], v[112:113] op_sel:[0,1,0]
	v_pk_mul_f32 v[106:107], v[84:85], v[54:55] op_sel:[0,1]
	v_pk_fma_f32 v[112:113], v[78:79], v[64:65], v[112:113] op_sel_hi:[1,0,1]
	v_pk_mul_f32 v[108:109], v[84:85], v[56:57] op_sel_hi:[1,0]
	v_pk_fma_f32 v[112:113], v[80:81], v[64:65], v[112:113] op_sel:[0,1,0]
	v_pk_mul_f32 v[110:111], v[84:85], v[56:57] op_sel:[0,1]
	v_pk_fma_f32 v[104:105], v[74:75], v[50:51], v[104:105] op_sel_hi:[1,0,1]
	v_add_f32_dpp v112, v112, v112 quad_perm:[1,0,3,2] row_mask:0xf bank_mask:0xf bound_ctrl:1
	v_add_f32_dpp v113, v113, v113 quad_perm:[1,0,3,2] row_mask:0xf bank_mask:0xf bound_ctrl:1
	v_pk_fma_f32 v[106:107], v[76:77], v[50:51], v[106:107] op_sel:[0,1,0]
	v_add_f32_dpp v112, v112, v112 quad_perm:[2,3,0,1] row_mask:0xf bank_mask:0xf bound_ctrl:1
	v_add_f32_dpp v113, v113, v113 quad_perm:[2,3,0,1] row_mask:0xf bank_mask:0xf bound_ctrl:1
	v_pk_fma_f32 v[108:109], v[78:79], v[52:53], v[108:109] op_sel_hi:[1,0,1]
	v_add_f32_dpp v112, v112, v112 row_half_mirror row_mask:0xf bank_mask:0xf bound_ctrl:1
	v_add_f32_dpp v113, v113, v113 row_half_mirror row_mask:0xf bank_mask:0xf bound_ctrl:1
	v_pk_fma_f32 v[110:111], v[80:81], v[52:53], v[110:111] op_sel:[0,1,0]
	v_add_f32_dpp v112, v112, v112 row_mirror row_mask:0xf bank_mask:0xf bound_ctrl:1
	v_add_f32_dpp v113, v113, v113 row_mirror row_mask:0xf bank_mask:0xf bound_ctrl:1
	v_pk_fma_f32 v[74:75], v[112:113], v[58:59], v[104:105] op_sel_hi:[1,0,1] neg_lo:[1,0,0] neg_hi:[1,0,0]
	v_pk_fma_f32 v[76:77], v[112:113], v[58:59], v[106:107] op_sel:[0,1,0] neg_lo:[1,0,0] neg_hi:[1,0,0]
	v_pk_mul_f32 v[114:115], v[74:75], v[46:47] op_sel_hi:[1,0]
	v_pk_fma_f32 v[78:79], v[112:113], v[60:61], v[108:109] op_sel_hi:[1,0,1] neg_lo:[1,0,0] neg_hi:[1,0,0]
	v_pk_fma_f32 v[114:115], v[76:77], v[46:47], v[114:115] op_sel:[0,1,0]
	v_pk_fma_f32 v[80:81], v[112:113], v[60:61], v[110:111] op_sel:[0,1,0] neg_lo:[1,0,0] neg_hi:[1,0,0]
	v_pk_fma_f32 v[114:115], v[78:79], v[48:49], v[114:115] op_sel_hi:[1,0,1]
	v_pk_fma_f32 v[114:115], v[80:81], v[48:49], v[114:115] op_sel:[0,1,0]
	ds_write_b64 v96, v[114:115] offset:19584
	s_waitcnt lgkmcnt(1)
; #define LAS __attribute__((address_space(3)))
; __device__ __forceinline__ void scan_job(LAS unsigned char* lds, const AP a, int l, int bl, int hd, int rh) {
;     ...
;             for (int st = 0; st < CH; ++st) {
;                 const f32x4 w = wN, kk = kkN, b = bN, k = kN, r = rN; const f32x2 v = vN;
;                 const int on = ((st + 1) & (CH - 1)) * 64;
;                 rN = *(const LAS f32x4*)(bp + on + o0); wN = *(const LAS f32x4*)(bp + VSZ + on + o0); kN = *(const LAS f32x4*)(bp + 2 * VSZ + on + o0); kkN = *(const LAS f32x4*)(bp + 4 * VSZ + on + o0); bN = *(const LAS f32x4*)(bp + 5 * VSZ + on + o0);
;                 vN = *(const LAS f32x2*)(bp + on + vo);
;                 const f32x2 kk0 = {kk.x, kk.y}, kk1 = {kk.z, kk.w}, w0 = {w.x, w.y}, w1 = {w.z, w.w}, b0 = {b.x, b.y}, b1 = {b.z, b.w}, k0 = {k.x, k.y}, k1 = {k.z, k.w}, r0 = {r.x, r.y}, r1 = {r.z, r.w};
;                 const f32x2 va = {v.x, v.x}, vb = {v.y, v.y};
;                 const f32x2 pa = sA0 * kk0 + sA1 * kk1, pb = sB0 * kk0 + sB1 * kk1;
;                 const float saA = -red16(pa.x + pa.y), saB = -red16(pb.x + pb.y);
;                 const f32x2 sav = {saA, saA}, sbv = {saB, saB};
;                 sA0 = sA0 * w0 + (sav * b0 + va * k0); sA1 = sA1 * w1 + (sav * b1 + va * k1);
;                 sB0 = sB0 * w0 + (sbv * b0 + vb * k0); sB1 = sB1 * w1 + (sbv * b1 + vb * k1);
;                 const f32x2 ya = sA0 * r0 + sA1 * r1, yb = sB0 * r0 + sB1 * r1;
;                 *(LAS f32x2*)(yl + st * 16 * YSTR) = (f32x2){ya.x + ya.y, yb.x + yb.y};
;             }
	ds_read_b128 v[46:49], v0 offset:2816
	ds_read_b128 v[50:53], v0 offset:6912
	ds_read_b128 v[54:57], v0 offset:11008
	ds_read_b128 v[62:65], v0 offset:19200
	ds_read_b128 v[58:61], v0 offset:23296
	ds_read_b64 v[84:85], v95 offset:15104
	v_pk_mul_f32 v[112:113], v[74:75], v[42:43] op_sel_hi:[1,0]
	v_pk_mul_f32 v[104:105], v[82:83], v[34:35] op_sel_hi:[1,0]
	v_pk_fma_f32 v[112:113], v[76:77], v[42:43], v[112:113] op_sel:[0,1,0]
	v_pk_mul_f32 v[106:107], v[82:83], v[34:35] op_sel:[0,1]
	v_pk_fma_f32 v[112:113], v[78:79], v[44:45], v[112:113] op_sel_hi:[1,0,1]
	v_pk_mul_f32 v[108:109], v[82:83], v[36:37] op_sel_hi:[1,0]
	v_pk_fma_f32 v[112:113], v[80:81], v[44:45], v[112:113] op_sel:[0,1,0]
	v_pk_mul_f32 v[110:111], v[82:83], v[36:37] op_sel:[0,1]
	v_pk_fma_f32 v[104:105], v[74:75], v[30:31], v[104:105] op_sel_hi:[1,0,1]
	v_add_f32_dpp v112, v112, v112 quad_perm:[1,0,3,2] row_mask:0xf bank_mask:0xf bound_ctrl:1
	v_add_f32_dpp v113, v113, v113 quad_perm:[1,0,3,2] row_mask:0xf bank_mask:0xf bound_ctrl:1
	v_pk_fma_f32 v[106:107], v[76:77], v[30:31], v[106:107] op_sel:[0,1,0]
	v_add_f32_dpp v112, v112, v112 quad_perm:[2,3,0,1] row_mask:0xf bank_mask:0xf bound_ctrl:1
	v_add_f32_dpp v113, v113, v113 quad_perm:[2,3,0,1] row_mask:0xf bank_mask:0xf bound_ctrl:1
	v_pk_fma_f32 v[108:109], v[78:79], v[32:33], v[108:109] op_sel_hi:[1,0,1]
	v_add_f32_dpp v112, v112, v112 row_half_mirror row_mask:0xf bank_mask:0xf bound_ctrl:1
	v_add_f32_dpp v113, v113, v113 row_half_mirror row_mask:0xf bank_mask:0xf bound_ctrl:1
	v_pk_fma_f32 v[110:111], v[80:81], v[32:33], v[110:111] op_sel:[0,1,0]
	v_add_f32_dpp v112, v112, v112 row_mirror row_mask:0xf bank_mask:0xf bound_ctrl:1
	v_add_f32_dpp v113, v113, v113 row_mirror row_mask:0xf bank_mask:0xf bound_ctrl:1
	v_pk_fma_f32 v[74:75], v[112:113], v[38:39], v[104:105] op_sel_hi:[1,0,1] neg_lo:[1,0,0] neg_hi:[1,0,0]
	v_pk_fma_f32 v[76:77], v[112:113], v[38:39], v[106:107] op_sel:[0,1,0] neg_lo:[1,0,0] neg_hi:[1,0,0]
	v_pk_mul_f32 v[114:115], v[74:75], v[26:27] op_sel_hi:[1,0]
	v_pk_fma_f32 v[78:79], v[112:113], v[40:41], v[108:109] op_sel_hi:[1,0,1] neg_lo:[1,0,0] neg_hi:[1,0,0]
	v_pk_fma_f32 v[114:115], v[76:77], v[26:27], v[114:115] op_sel:[0,1,0]
	v_pk_fma_f32 v[80:81], v[112:113], v[40:41], v[110:111] op_sel:[0,1,0] neg_lo:[1,0,0] neg_hi:[1,0,0]
	v_pk_fma_f32 v[114:115], v[78:79], v[28:29], v[114:115] op_sel_hi:[1,0,1]
	v_pk_fma_f32 v[114:115], v[80:81], v[28:29], v[114:115] op_sel:[0,1,0]
	ds_write_b64 v96, v[114:115] offset:21760
	s_waitcnt lgkmcnt(1)
	ds_read_b128 v[26:29], v0 offset:3072
	ds_read_b128 v[30:33], v0 offset:7168
	ds_read_b128 v[34:37], v0 offset:11264
	ds_read_b128 v[42:45], v0 offset:19456
	ds_read_b128 v[38:41], v0 offset:23552
	ds_read_b64 v[82:83], v95 offset:15360
	v_pk_mul_f32 v[112:113], v[74:75], v[62:63] op_sel_hi:[1,0]
	v_pk_mul_f32 v[104:105], v[84:85], v[54:55] op_sel_hi:[1,0]
	v_pk_fma_f32 v[112:113], v[76:77], v[62:63], v[112:113] op_sel:[0,1,0]
	v_pk_mul_f32 v[106:107], v[84:85], v[54:55] op_sel:[0,1]
	v_pk_fma_f32 v[112:113], v[78:79], v[64:65], v[112:113] op_sel_hi:[1,0,1]
	v_pk_mul_f32 v[108:109], v[84:85], v[56:57] op_sel_hi:[1,0]
	v_pk_fma_f32 v[112:113], v[80:81], v[64:65], v[112:113] op_sel:[0,1,0]
	v_pk_mul_f32 v[110:111], v[84:85], v[56:57] op_sel:[0,1]
	v_pk_fma_f32 v[104:105], v[74:75], v[50:51], v[104:105] op_sel_hi:[1,0,1]
	v_add_f32_dpp v112, v112, v112 quad_perm:[1,0,3,2] row_mask:0xf bank_mask:0xf bound_ctrl:1
	v_add_f32_dpp v113, v113, v113 quad_perm:[1,0,3,2] row_mask:0xf bank_mask:0xf bound_ctrl:1
	v_pk_fma_f32 v[106:107], v[76:77], v[50:51], v[106:107] op_sel:[0,1,0]
	v_add_f32_dpp v112, v112, v112 quad_perm:[2,3,0,1] row_mask:0xf bank_mask:0xf bound_ctrl:1
	v_add_f32_dpp v113, v113, v113 quad_perm:[2,3,0,1] row_mask:0xf bank_mask:0xf bound_ctrl:1
	v_pk_fma_f32 v[108:109], v[78:79], v[52:53], v[108:109] op_sel_hi:[1,0,1]
	v_add_f32_dpp v112, v112, v112 row_half_mirror row_mask:0xf bank_mask:0xf bound_ctrl:1
	v_add_f32_dpp v113, v113, v113 row_half_mirror row_mask:0xf bank_mask:0xf bound_ctrl:1
	v_pk_fma_f32 v[110:111], v[80:81], v[52:53], v[110:111] op_sel:[0,1,0]
	v_add_f32_dpp v112, v112, v112 row_mirror row_mask:0xf bank_mask:0xf bound_ctrl:1
	v_add_f32_dpp v113, v113, v113 row_mirror row_mask:0xf bank_mask:0xf bound_ctrl:1
	v_pk_fma_f32 v[74:75], v[112:113], v[58:59], v[104:105] op_sel_hi:[1,0,1] neg_lo:[1,0,0] neg_hi:[1,0,0]
	v_pk_fma_f32 v[76:77], v[112:113], v[58:59], v[106:107] op_sel:[0,1,0] neg_lo:[1,0,0] neg_hi:[1,0,0]
	v_pk_mul_f32 v[114:115], v[74:75], v[46:47] op_sel_hi:[1,0]
	v_pk_fma_f32 v[78:79], v[112:113], v[60:61], v[108:109] op_sel_hi:[1,0,1] neg_lo:[1,0,0] neg_hi:[1,0,0]
	v_pk_fma_f32 v[114:115], v[76:77], v[46:47], v[114:115] op_sel:[0,1,0]
	v_pk_fma_f32 v[80:81], v[112:113], v[60:61], v[110:111] op_sel:[0,1,0] neg_lo:[1,0,0] neg_hi:[1,0,0]
	v_pk_fma_f32 v[114:115], v[78:79], v[48:49], v[114:115] op_sel_hi:[1,0,1]
	v_pk_fma_f32 v[114:115], v[80:81], v[48:49], v[114:115] op_sel:[0,1,0]
	ds_write_b64 v96, v[114:115] offset:23936
	s_waitcnt lgkmcnt(1)
; #define LAS __attribute__((address_space(3)))
; __device__ __forceinline__ void scan_job(LAS unsigned char* lds, const AP a, int l, int bl, int hd, int rh) {
;     ...
;             for (int st = 0; st < CH; ++st) {
;                 const f32x4 w = wN, kk = kkN, b = bN, k = kN, r = rN; const f32x2 v = vN;
;                 const int on = ((st + 1) & (CH - 1)) * 64;
;                 rN = *(const LAS f32x4*)(bp + on + o0); wN = *(const LAS f32x4*)(bp + VSZ + on + o0); kN = *(const LAS f32x4*)(bp + 2 * VSZ + on + o0); kkN = *(const LAS f32x4*)(bp + 4 * VSZ + on + o0); bN = *(const LAS f32x4*)(bp + 5 * VSZ + on + o0);
;                 vN = *(const LAS f32x2*)(bp + on + vo);
;                 const f32x2 kk0 = {kk.x, kk.y}, kk1 = {kk.z, kk.w}, w0 = {w.x, w.y}, w1 = {w.z, w.w}, b0 = {b.x, b.y}, b1 = {b.z, b.w}, k0 = {k.x, k.y}, k1 = {k.z, k.w}, r0 = {r.x, r.y}, r1 = {r.z, r.w};
;                 const f32x2 va = {v.x, v.x}, vb = {v.y, v.y};
;                 const f32x2 pa = sA0 * kk0 + sA1 * kk1, pb = sB0 * kk0 + sB1 * kk1;
;                 const float saA = -red16(pa.x + pa.y), saB = -red16(pb.x + pb.y);
;                 const f32x2 sav = {saA, saA}, sbv = {saB, saB};
;                 sA0 = sA0 * w0 + (sav * b0 + va * k0); sA1 = sA1 * w1 + (sav * b1 + va * k1);
;                 sB0 = sB0 * w0 + (sbv * b0 + vb * k0); sB1 = sB1 * w1 + (sbv * b1 + vb * k1);
;                 const f32x2 ya = sA0 * r0 + sA1 * r1, yb = sB0 * r0 + sB1 * r1;
;                 *(LAS f32x2*)(yl + st * 16 * YSTR) = (f32x2){ya.x + ya.y, yb.x + yb.y};
;             }
	ds_read_b128 v[46:49], v0 offset:3328
	ds_read_b128 v[50:53], v0 offset:7424
	ds_read_b128 v[54:57], v0 offset:11520
	ds_read_b128 v[62:65], v0 offset:19712
	ds_read_b128 v[58:61], v0 offset:23808
	ds_read_b64 v[84:85], v95 offset:15616
	v_pk_mul_f32 v[112:113], v[74:75], v[42:43] op_sel_hi:[1,0]
	v_pk_mul_f32 v[104:105], v[82:83], v[34:35] op_sel_hi:[1,0]
	v_pk_fma_f32 v[112:113], v[76:77], v[42:43], v[112:113] op_sel:[0,1,0]
	v_pk_mul_f32 v[106:107], v[82:83], v[34:35] op_sel:[0,1]
	v_pk_fma_f32 v[112:113], v[78:79], v[44:45], v[112:113] op_sel_hi:[1,0,1]
	v_pk_mul_f32 v[108:109], v[82:83], v[36:37] op_sel_hi:[1,0]
	v_pk_fma_f32 v[112:113], v[80:81], v[44:45], v[112:113] op_sel:[0,1,0]
	v_pk_mul_f32 v[110:111], v[82:83], v[36:37] op_sel:[0,1]
	v_pk_fma_f32 v[104:105], v[74:75], v[30:31], v[104:105] op_sel_hi:[1,0,1]
	v_add_f32_dpp v112, v112, v112 quad_perm:[1,0,3,2] row_mask:0xf bank_mask:0xf bound_ctrl:1
	v_add_f32_dpp v113, v113, v113 quad_perm:[1,0,3,2] row_mask:0xf bank_mask:0xf bound_ctrl:1
	v_pk_fma_f32 v[106:107], v[76:77], v[30:31], v[106:107] op_sel:[0,1,0]
	v_add_f32_dpp v112, v112, v112 quad_perm:[2,3,0,1] row_mask:0xf bank_mask:0xf bound_ctrl:1
	v_add_f32_dpp v113, v113, v113 quad_perm:[2,3,0,1] row_mask:0xf bank_mask:0xf bound_ctrl:1
	v_pk_fma_f32 v[108:109], v[78:79], v[32:33], v[108:109] op_sel_hi:[1,0,1]
	v_add_f32_dpp v112, v112, v112 row_half_mirror row_mask:0xf bank_mask:0xf bound_ctrl:1
	v_add_f32_dpp v113, v113, v113 row_half_mirror row_mask:0xf bank_mask:0xf bound_ctrl:1
	v_pk_fma_f32 v[110:111], v[80:81], v[32:33], v[110:111] op_sel:[0,1,0]
	v_add_f32_dpp v112, v112, v112 row_mirror row_mask:0xf bank_mask:0xf bound_ctrl:1
	v_add_f32_dpp v113, v113, v113 row_mirror row_mask:0xf bank_mask:0xf bound_ctrl:1
	v_pk_fma_f32 v[74:75], v[112:113], v[38:39], v[104:105] op_sel_hi:[1,0,1] neg_lo:[1,0,0] neg_hi:[1,0,0]
	v_pk_fma_f32 v[76:77], v[112:113], v[38:39], v[106:107] op_sel:[0,1,0] neg_lo:[1,0,0] neg_hi:[1,0,0]
	v_pk_mul_f32 v[114:115], v[74:75], v[26:27] op_sel_hi:[1,0]
	v_pk_fma_f32 v[78:79], v[112:113], v[40:41], v[108:109] op_sel_hi:[1,0,1] neg_lo:[1,0,0] neg_hi:[1,0,0]
	v_pk_fma_f32 v[114:115], v[76:77], v[26:27], v[114:115] op_sel:[0,1,0]
	v_pk_fma_f32 v[80:81], v[112:113], v[40:41], v[110:111] op_sel:[0,1,0] neg_lo:[1,0,0] neg_hi:[1,0,0]
	v_pk_fma_f32 v[114:115], v[78:79], v[28:29], v[114:115] op_sel_hi:[1,0,1]
	v_pk_fma_f32 v[114:115], v[80:81], v[28:29], v[114:115] op_sel:[0,1,0]
	ds_write_b64 v96, v[114:115] offset:26112
	s_waitcnt lgkmcnt(1)
	ds_read_b128 v[26:29], v0 offset:3584
	ds_read_b128 v[30:33], v0 offset:7680
	ds_read_b128 v[34:37], v0 offset:11776
	ds_read_b128 v[42:45], v0 offset:19968
	ds_read_b128 v[38:41], v0 offset:24064
	ds_read_b64 v[82:83], v95 offset:15872
	v_pk_mul_f32 v[112:113], v[74:75], v[62:63] op_sel_hi:[1,0]
	v_pk_mul_f32 v[104:105], v[84:85], v[54:55] op_sel_hi:[1,0]
	v_pk_fma_f32 v[112:113], v[76:77], v[62:63], v[112:113] op_sel:[0,1,0]
	v_pk_mul_f32 v[106:107], v[84:85], v[54:55] op_sel:[0,1]
	v_pk_fma_f32 v[112:113], v[78:79], v[64:65], v[112:113] op_sel_hi:[1,0,1]
	v_pk_mul_f32 v[108:109], v[84:85], v[56:57] op_sel_hi:[1,0]
	v_pk_fma_f32 v[112:113], v[80:81], v[64:65], v[112:113] op_sel:[0,1,0]
	v_pk_mul_f32 v[110:111], v[84:85], v[56:57] op_sel:[0,1]
	v_pk_fma_f32 v[104:105], v[74:75], v[50:51], v[104:105] op_sel_hi:[1,0,1]
	v_add_f32_dpp v112, v112, v112 quad_perm:[1,0,3,2] row_mask:0xf bank_mask:0xf bound_ctrl:1
	v_add_f32_dpp v113, v113, v113 quad_perm:[1,0,3,2] row_mask:0xf bank_mask:0xf bound_ctrl:1
	v_pk_fma_f32 v[106:107], v[76:77], v[50:51], v[106:107] op_sel:[0,1,0]
	v_add_f32_dpp v112, v112, v112 quad_perm:[2,3,0,1] row_mask:0xf bank_mask:0xf bound_ctrl:1
	v_add_f32_dpp v113, v113, v113 quad_perm:[2,3,0,1] row_mask:0xf bank_mask:0xf bound_ctrl:1
	v_pk_fma_f32 v[108:109], v[78:79], v[52:53], v[108:109] op_sel_hi:[1,0,1]
	v_add_f32_dpp v112, v112, v112 row_half_mirror row_mask:0xf bank_mask:0xf bound_ctrl:1
	v_add_f32_dpp v113, v113, v113 row_half_mirror row_mask:0xf bank_mask:0xf bound_ctrl:1
	v_pk_fma_f32 v[110:111], v[80:81], v[52:53], v[110:111] op_sel:[0,1,0]
	v_add_f32_dpp v112, v112, v112 row_mirror row_mask:0xf bank_mask:0xf bound_ctrl:1
	v_add_f32_dpp v113, v113, v113 row_mirror row_mask:0xf bank_mask:0xf bound_ctrl:1
	v_pk_fma_f32 v[74:75], v[112:113], v[58:59], v[104:105] op_sel_hi:[1,0,1] neg_lo:[1,0,0] neg_hi:[1,0,0]
	v_pk_fma_f32 v[76:77], v[112:113], v[58:59], v[106:107] op_sel:[0,1,0] neg_lo:[1,0,0] neg_hi:[1,0,0]
	v_pk_mul_f32 v[114:115], v[74:75], v[46:47] op_sel_hi:[1,0]
	v_pk_fma_f32 v[78:79], v[112:113], v[60:61], v[108:109] op_sel_hi:[1,0,1] neg_lo:[1,0,0] neg_hi:[1,0,0]
	v_pk_fma_f32 v[114:115], v[76:77], v[46:47], v[114:115] op_sel:[0,1,0]
	v_pk_fma_f32 v[80:81], v[112:113], v[60:61], v[110:111] op_sel:[0,1,0] neg_lo:[1,0,0] neg_hi:[1,0,0]
	v_pk_fma_f32 v[114:115], v[78:79], v[48:49], v[114:115] op_sel_hi:[1,0,1]
	v_pk_fma_f32 v[114:115], v[80:81], v[48:49], v[114:115] op_sel:[0,1,0]
	ds_write_b64 v96, v[114:115] offset:28288
	s_waitcnt lgkmcnt(1)
; #define LAS __attribute__((address_space(3)))
; __device__ __forceinline__ void scan_job(LAS unsigned char* lds, const AP a, int l, int bl, int hd, int rh) {
;     ...
;             for (int st = 0; st < CH; ++st) {
;                 const f32x4 w = wN, kk = kkN, b = bN, k = kN, r = rN; const f32x2 v = vN;
;                 const int on = ((st + 1) & (CH - 1)) * 64;
;                 rN = *(const LAS f32x4*)(bp + on + o0); wN = *(const LAS f32x4*)(bp + VSZ + on + o0); kN = *(const LAS f32x4*)(bp + 2 * VSZ + on + o0); kkN = *(const LAS f32x4*)(bp + 4 * VSZ + on + o0); bN = *(const LAS f32x4*)(bp + 5 * VSZ + on + o0);
;                 vN = *(const LAS f32x2*)(bp + on + vo);
;                 const f32x2 kk0 = {kk.x, kk.y}, kk1 = {kk.z, kk.w}, w0 = {w.x, w.y}, w1 = {w.z, w.w}, b0 = {b.x, b.y}, b1 = {b.z, b.w}, k0 = {k.x, k.y}, k1 = {k.z, k.w}, r0 = {r.x, r.y}, r1 = {r.z, r.w};
;                 const f32x2 va = {v.x, v.x}, vb = {v.y, v.y};
;                 const f32x2 pa = sA0 * kk0 + sA1 * kk1, pb = sB0 * kk0 + sB1 * kk1;
;                 const float saA = -red16(pa.x + pa.y), saB = -red16(pb.x + pb.y);
;                 const f32x2 sav = {saA, saA}, sbv = {saB, saB};
;                 sA0 = sA0 * w0 + (sav * b0 + va * k0); sA1 = sA1 * w1 + (sav * b1 + va * k1);
;                 sB0 = sB0 * w0 + (sbv * b0 + vb * k0); sB1 = sB1 * w1 + (sbv * b1 + vb * k1);
;                 const f32x2 ya = sA0 * r0 + sA1 * r1, yb = sB0 * r0 + sB1 * r1;
;                 *(LAS f32x2*)(yl + st * 16 * YSTR) = (f32x2){ya.x + ya.y, yb.x + yb.y};
;             }
	ds_read_b128 v[46:49], v0 offset:3840
	ds_read_b128 v[50:53], v0 offset:7936
	ds_read_b128 v[54:57], v0 offset:12032
	ds_read_b128 v[62:65], v0 offset:20224
	ds_read_b128 v[58:61], v0 offset:24320
	ds_read_b64 v[84:85], v95 offset:16128
	v_pk_mul_f32 v[112:113], v[74:75], v[42:43] op_sel_hi:[1,0]
	v_pk_mul_f32 v[104:105], v[82:83], v[34:35] op_sel_hi:[1,0]
	v_pk_fma_f32 v[112:113], v[76:77], v[42:43], v[112:113] op_sel:[0,1,0]
	v_pk_mul_f32 v[106:107], v[82:83], v[34:35] op_sel:[0,1]
	v_pk_fma_f32 v[112:113], v[78:79], v[44:45], v[112:113] op_sel_hi:[1,0,1]
	v_pk_mul_f32 v[108:109], v[82:83], v[36:37] op_sel_hi:[1,0]
	v_pk_fma_f32 v[112:113], v[80:81], v[44:45], v[112:113] op_sel:[0,1,0]
	v_pk_mul_f32 v[110:111], v[82:83], v[36:37] op_sel:[0,1]
	v_pk_fma_f32 v[104:105], v[74:75], v[30:31], v[104:105] op_sel_hi:[1,0,1]
	v_add_f32_dpp v112, v112, v112 quad_perm:[1,0,3,2] row_mask:0xf bank_mask:0xf bound_ctrl:1
	v_add_f32_dpp v113, v113, v113 quad_perm:[1,0,3,2] row_mask:0xf bank_mask:0xf bound_ctrl:1
	v_pk_fma_f32 v[106:107], v[76:77], v[30:31], v[106:107] op_sel:[0,1,0]
	v_add_f32_dpp v112, v112, v112 quad_perm:[2,3,0,1] row_mask:0xf bank_mask:0xf bound_ctrl:1
	v_add_f32_dpp v113, v113, v113 quad_perm:[2,3,0,1] row_mask:0xf bank_mask:0xf bound_ctrl:1
	v_pk_fma_f32 v[108:109], v[78:79], v[32:33], v[108:109] op_sel_hi:[1,0,1]
	v_add_f32_dpp v112, v112, v112 row_half_mirror row_mask:0xf bank_mask:0xf bound_ctrl:1
	v_add_f32_dpp v113, v113, v113 row_half_mirror row_mask:0xf bank_mask:0xf bound_ctrl:1
	v_pk_fma_f32 v[110:111], v[80:81], v[32:33], v[110:111] op_sel:[0,1,0]
	v_add_f32_dpp v112, v112, v112 row_mirror row_mask:0xf bank_mask:0xf bound_ctrl:1
	v_add_f32_dpp v113, v113, v113 row_mirror row_mask:0xf bank_mask:0xf bound_ctrl:1
	v_pk_fma_f32 v[74:75], v[112:113], v[38:39], v[104:105] op_sel_hi:[1,0,1] neg_lo:[1,0,0] neg_hi:[1,0,0]
	v_pk_fma_f32 v[76:77], v[112:113], v[38:39], v[106:107] op_sel:[0,1,0] neg_lo:[1,0,0] neg_hi:[1,0,0]
	v_pk_mul_f32 v[114:115], v[74:75], v[26:27] op_sel_hi:[1,0]
	v_pk_fma_f32 v[78:79], v[112:113], v[40:41], v[108:109] op_sel_hi:[1,0,1] neg_lo:[1,0,0] neg_hi:[1,0,0]
	v_pk_fma_f32 v[114:115], v[76:77], v[26:27], v[114:115] op_sel:[0,1,0]
	v_pk_fma_f32 v[80:81], v[112:113], v[40:41], v[110:111] op_sel:[0,1,0] neg_lo:[1,0,0] neg_hi:[1,0,0]
	v_pk_fma_f32 v[114:115], v[78:79], v[28:29], v[114:115] op_sel_hi:[1,0,1]
	v_pk_fma_f32 v[114:115], v[80:81], v[28:29], v[114:115] op_sel:[0,1,0]
	ds_write_b64 v96, v[114:115] offset:30464
	s_waitcnt lgkmcnt(1)
	v_pk_mul_f32 v[112:113], v[74:75], v[62:63] op_sel_hi:[1,0]
	v_pk_mul_f32 v[104:105], v[84:85], v[54:55] op_sel_hi:[1,0]
	v_pk_fma_f32 v[112:113], v[76:77], v[62:63], v[112:113] op_sel:[0,1,0]
	v_pk_mul_f32 v[106:107], v[84:85], v[54:55] op_sel:[0,1]
	v_pk_fma_f32 v[112:113], v[78:79], v[64:65], v[112:113] op_sel_hi:[1,0,1]
	v_pk_mul_f32 v[108:109], v[84:85], v[56:57] op_sel_hi:[1,0]
	v_pk_fma_f32 v[112:113], v[80:81], v[64:65], v[112:113] op_sel:[0,1,0]
	v_pk_mul_f32 v[110:111], v[84:85], v[56:57] op_sel:[0,1]
	v_pk_fma_f32 v[104:105], v[74:75], v[50:51], v[104:105] op_sel_hi:[1,0,1]
	v_add_f32_dpp v112, v112, v112 quad_perm:[1,0,3,2] row_mask:0xf bank_mask:0xf bound_ctrl:1
	v_add_f32_dpp v113, v113, v113 quad_perm:[1,0,3,2] row_mask:0xf bank_mask:0xf bound_ctrl:1
	v_pk_fma_f32 v[106:107], v[76:77], v[50:51], v[106:107] op_sel:[0,1,0]
	v_add_f32_dpp v112, v112, v112 quad_perm:[2,3,0,1] row_mask:0xf bank_mask:0xf bound_ctrl:1
	v_add_f32_dpp v113, v113, v113 quad_perm:[2,3,0,1] row_mask:0xf bank_mask:0xf bound_ctrl:1
	v_pk_fma_f32 v[108:109], v[78:79], v[52:53], v[108:109] op_sel_hi:[1,0,1]
	v_add_f32_dpp v112, v112, v112 row_half_mirror row_mask:0xf bank_mask:0xf bound_ctrl:1
	v_add_f32_dpp v113, v113, v113 row_half_mirror row_mask:0xf bank_mask:0xf bound_ctrl:1
	v_pk_fma_f32 v[110:111], v[80:81], v[52:53], v[110:111] op_sel:[0,1,0]
	v_add_f32_dpp v112, v112, v112 row_mirror row_mask:0xf bank_mask:0xf bound_ctrl:1
	v_add_f32_dpp v113, v113, v113 row_mirror row_mask:0xf bank_mask:0xf bound_ctrl:1
	v_pk_fma_f32 v[74:75], v[112:113], v[58:59], v[104:105] op_sel_hi:[1,0,1] neg_lo:[1,0,0] neg_hi:[1,0,0]
	v_pk_fma_f32 v[76:77], v[112:113], v[58:59], v[106:107] op_sel:[0,1,0] neg_lo:[1,0,0] neg_hi:[1,0,0]
	v_pk_mul_f32 v[114:115], v[74:75], v[46:47] op_sel_hi:[1,0]
	v_pk_fma_f32 v[78:79], v[112:113], v[60:61], v[108:109] op_sel_hi:[1,0,1] neg_lo:[1,0,0] neg_hi:[1,0,0]
	v_pk_fma_f32 v[114:115], v[76:77], v[46:47], v[114:115] op_sel:[0,1,0]
	v_pk_fma_f32 v[80:81], v[112:113], v[60:61], v[110:111] op_sel:[0,1,0] neg_lo:[1,0,0] neg_hi:[1,0,0]
	v_pk_fma_f32 v[114:115], v[78:79], v[48:49], v[114:115] op_sel_hi:[1,0,1]
	v_pk_fma_f32 v[114:115], v[80:81], v[48:49], v[114:115] op_sel:[0,1,0]
	ds_write_b64 v96, v[114:115] offset:32640
	s_setprio 0
